# gla_combine rewritten by hand: DPP/permlane wave reduction instead of LDS shuffles, 4 token buffers in flight
# speedup vs baseline: 1.0915x; 1.0064x over previous
.LBB0_1227:
	s_or_b64 exec, exec, s[0:1]
	s_waitcnt lgkmcnt(0)
	v_mov_b32_e32 v0, v176
	s_barrier
	v_readlane_b32 s1, v254, 41
	s_nop 3
	s_cmpk_eq_i32 s1, 0x200
	s_cbranch_scc1 .Lcomb_fast
	s_mov_b32 s0, s94
	v_ashrrev_i32_e32 v6, 6, v0
	s_mov_b32 s1, 0xc000
	v_lshl_add_u32 v26, s0, 2, v6
	v_cmp_gt_i32_e32 vcc, s1, v26
	s_and_saveexec_b64 s[2:3], vcc
	v_readlane_b32 s20, v254, 38
	v_readlane_b32 s21, v254, 39
	s_cbranch_execz .LBB0_1242
	v_readlane_b32 s4, v254, 59
	v_readlane_b32 s5, v254, 60
	s_and_b64 s[4:5], s[4:5], exec
	v_readlane_b32 s4, v253, 18
	s_cselect_b32 s1, 0x400, 0
	v_readlane_b32 s12, v253, 26
	v_lshlrev_b32_e32 v0, 2, v0
	v_readlane_b32 s5, v253, 19
	v_readlane_b32 s13, v253, 27
	s_add_u32 s4, s12, s1
	v_and_b32_e32 v4, 0xfc, v0
	s_addc_u32 s5, s13, 0
	v_lshlrev_b32_e32 v0, 2, v4
	global_load_dwordx4 v[0:3], v0, s[4:5]
	v_cmp_lt_i32_e32 vcc, v191, v185
	v_readlane_b32 s8, v253, 22
	v_readlane_b32 s9, v253, 23
	v_cndmask_b32_e32 v5, v183, v191, vcc
	v_cmp_lt_i32_e32 vcc, v190, v185
	v_lshlrev_b32_e32 v6, 8, v6
	v_lshlrev_b32_e32 v5, 2, v5
	v_cndmask_b32_e32 v7, v183, v190, vcc
	v_cmp_lt_i32_e32 vcc, v189, v185
	v_lshlrev_b32_e32 v40, 2, v7
	v_lshl_add_u32 v45, s0, 10, v6
	v_cndmask_b32_e32 v7, v183, v189, vcc
	v_cmp_lt_i32_e32 vcc, v188, v185
	v_lshlrev_b32_e32 v41, 2, v7
	s_mov_b64 s[8:9], 0
	v_cndmask_b32_e32 v7, v183, v188, vcc
	v_cmp_lt_i32_e32 vcc, v187, v185
	v_lshlrev_b32_e32 v42, 2, v7
	v_readlane_b32 s6, v253, 20
	v_cndmask_b32_e32 v7, v183, v187, vcc
	v_cmp_lt_i32_e32 vcc, v186, v185
	v_lshlrev_b32_e32 v43, 2, v7
	v_readlane_b32 s7, v253, 21
	v_cndmask_b32_e32 v7, v183, v186, vcc
	v_lshlrev_b32_e32 v44, 2, v7
	v_readlane_b32 s10, v253, 24
	v_readlane_b32 s11, v253, 25
	v_readlane_b32 s14, v253, 28
	v_readlane_b32 s15, v253, 29
	v_readlane_b32 s16, v253, 30
	v_readlane_b32 s17, v253, 31
	v_readlane_b32 s18, v253, 32
	v_readlane_b32 s19, v253, 33
	s_branch .LBB0_1230

.Lcomb_fast:
	v_readlane_b32 s4, v254, 59
	v_readlane_b32 s5, v254, 60
	s_and_b64 s[4:5], s[4:5], exec
	v_readlane_b32 s4, v253, 26
	s_cselect_b32 s1, 0x400, 0
	v_readlane_b32 s5, v253, 27
	v_and_b32_e32 v5, 63, v176
	v_lshlrev_b32_e32 v6, 4, v5
	s_add_u32 s4, s4, s1
	s_addc_u32 s5, s5, 0
	global_load_dwordx4 v[0:3], v6, s[4:5]
	v_lshrrev_b32_e32 v6, 6, v176
	v_lshlrev_b32_e32 v6, 9, v6
	v_lshl_add_u32 v4, v5, 3, v6
	v_readlane_b32 s6, v254, 27
	v_readlane_b32 s7, v254, 28
	v_readlane_b32 s8, v254, 29
	v_readlane_b32 s9, v254, 30
	s_lshl_b32 s0, s94, 11
	s_mul_i32 s1, s94, 0x1800
	s_add_u32 s6, s6, s0
	s_addc_u32 s7, s7, 0
	s_add_u32 s8, s8, s0
	s_addc_u32 s9, s9, 0
	s_add_u32 s14, s88, s0
	s_addc_u32 s15, s89, 0
	s_add_u32 s10, s90, s1
	s_addc_u32 s11, s91, 0
	s_add_u32 s10, s10, 0x1000
	s_addc_u32 s11, s11, 0
	s_mov_b32 s20, 0xbfb8aa3b
	s_mov_b32 s0, 0
	s_lshl_b32 s1, s0, 20
	s_add_u32 s16, s6, s1
	s_addc_u32 s17, s7, 0
	s_add_u32 s18, s8, s1
	s_addc_u32 s19, s9, 0
	s_mul_i32 s1, s0, 0x300000
	s_add_u32 s12, s10, s1
	s_addc_u32 s13, s11, 0
	global_load_dwordx2 v[8:9], v4, s[16:17] nt
	global_load_dwordx2 v[10:11], v4, s[18:19] nt
	global_load_dwordx2 v[12:13], v4, s[12:13] nt
	s_mov_b32 s0, 1
	s_lshl_b32 s1, s0, 20
	s_add_u32 s16, s6, s1
	s_addc_u32 s17, s7, 0
	s_add_u32 s18, s8, s1
	s_addc_u32 s19, s9, 0
	s_mul_i32 s1, s0, 0x300000
	s_add_u32 s12, s10, s1
	s_addc_u32 s13, s11, 0
	global_load_dwordx2 v[14:15], v4, s[16:17] nt
	global_load_dwordx2 v[16:17], v4, s[18:19] nt
	global_load_dwordx2 v[18:19], v4, s[12:13] nt
	s_mov_b32 s0, 2
	s_lshl_b32 s1, s0, 20
	s_add_u32 s16, s6, s1
	s_addc_u32 s17, s7, 0
	s_add_u32 s18, s8, s1
	s_addc_u32 s19, s9, 0
	s_mul_i32 s1, s0, 0x300000
	s_add_u32 s12, s10, s1
	s_addc_u32 s13, s11, 0
	global_load_dwordx2 v[20:21], v4, s[16:17] nt
	global_load_dwordx2 v[22:23], v4, s[18:19] nt
	global_load_dwordx2 v[24:25], v4, s[12:13] nt
	s_mov_b32 s0, 3
	s_lshl_b32 s1, s0, 20
	s_add_u32 s16, s6, s1
	s_addc_u32 s17, s7, 0
	s_add_u32 s18, s8, s1
	s_addc_u32 s19, s9, 0
	s_mul_i32 s1, s0, 0x300000
	s_add_u32 s12, s10, s1
	s_addc_u32 s13, s11, 0
	global_load_dwordx2 v[26:27], v4, s[16:17] nt
	global_load_dwordx2 v[28:29], v4, s[18:19] nt
	global_load_dwordx2 v[30:31], v4, s[12:13] nt
	s_waitcnt vmcnt(9)
	v_lshlrev_b32_e32 v32, 16, v8
	v_and_b32_e32 v33, 0xffff0000, v8
	v_lshlrev_b32_e32 v34, 16, v10
	v_and_b32_e32 v35, 0xffff0000, v10
	v_lshlrev_b32_e32 v36, 16, v9
	v_and_b32_e32 v37, 0xffff0000, v9
	v_lshlrev_b32_e32 v38, 16, v11
	v_and_b32_e32 v39, 0xffff0000, v11
	v_pk_add_f32 v[32:33], v[32:33], v[34:35]
	v_pk_add_f32 v[36:37], v[36:37], v[38:39]
	v_lshlrev_b32_e32 v44, 16, v12
	v_and_b32_e32 v45, 0xffff0000, v12
	v_lshlrev_b32_e32 v46, 16, v13
	v_and_b32_e32 v47, 0xffff0000, v13
	s_mov_b32 s0, 4
	s_lshl_b32 s1, s0, 20
	s_add_u32 s16, s6, s1
	s_addc_u32 s17, s7, 0
	s_add_u32 s18, s8, s1
	s_addc_u32 s19, s9, 0
	s_mul_i32 s1, s0, 0x300000
	s_add_u32 s12, s10, s1
	s_addc_u32 s13, s11, 0
	global_load_dwordx2 v[8:9], v4, s[16:17] nt
	global_load_dwordx2 v[10:11], v4, s[18:19] nt
	global_load_dwordx2 v[12:13], v4, s[12:13] nt
	v_pk_mul_f32 v[34:35], v[32:33], v[32:33]
	v_pk_mul_f32 v[38:39], v[36:37], v[36:37]
	v_add_f32_e32 v34, v34, v35
	v_add_f32_e32 v34, v34, v38
	v_add_f32_e32 v34, v34, v39
	s_nop 1
	v_add_f32_dpp v34, v34, v34 row_ror:8 row_mask:0xf bank_mask:0xf
	s_nop 1
	v_add_f32_dpp v34, v34, v34 row_ror:4 row_mask:0xf bank_mask:0xf
	s_nop 1
	v_add_f32_dpp v34, v34, v34 row_ror:2 row_mask:0xf bank_mask:0xf
	s_nop 1
	v_add_f32_dpp v34, v34, v34 row_ror:1 row_mask:0xf bank_mask:0xf
	v_mov_b32_e32 v35, v34
	s_nop 1
	v_permlane16_swap_b32 v34, v35
	v_add_f32_e32 v34, v34, v35
	v_mov_b32_e32 v35, v34
	s_nop 1
	v_permlane32_swap_b32 v34, v35
	v_add_f32_e32 v34, v34, v35
	v_mul_f32_e32 v52, 0xbfb8aa3b, v44
	v_fma_f32 v53, v44, s20, -v52
	v_rndne_f32_e32 v54, v52
	v_fmac_f32_e32 v53, 0xb2a5705f, v44
	v_sub_f32_e32 v52, v52, v54
	v_add_f32_e32 v52, v52, v53
	v_exp_f32_e32 v48, v52
	v_cvt_i32_f32_e32 v54, v54
	v_cmp_nlt_f32_e32 vcc, 0x42ce8ed0, v44
	v_ldexp_f32 v48, v48, v54
	s_nop 0
	v_cndmask_b32_e32 v48, 0, v48, vcc
	v_cmp_ngt_f32_e32 vcc, 0xc2b17218, v44
	s_nop 1
	v_cndmask_b32_e32 v48, v192, v48, vcc
	v_mul_f32_e32 v52, 0xbfb8aa3b, v45
	v_fma_f32 v53, v45, s20, -v52
	v_rndne_f32_e32 v54, v52
	v_fmac_f32_e32 v53, 0xb2a5705f, v45
	v_sub_f32_e32 v52, v52, v54
	v_add_f32_e32 v52, v52, v53
	v_exp_f32_e32 v49, v52
	v_cvt_i32_f32_e32 v54, v54
	v_cmp_nlt_f32_e32 vcc, 0x42ce8ed0, v45
	v_ldexp_f32 v49, v49, v54
	s_nop 0
	v_cndmask_b32_e32 v49, 0, v49, vcc
	v_cmp_ngt_f32_e32 vcc, 0xc2b17218, v45
	s_nop 1
	v_cndmask_b32_e32 v49, v192, v49, vcc
	v_mul_f32_e32 v52, 0xbfb8aa3b, v46
	v_fma_f32 v53, v46, s20, -v52
	v_rndne_f32_e32 v54, v52
	v_fmac_f32_e32 v53, 0xb2a5705f, v46
	v_sub_f32_e32 v52, v52, v54
	v_add_f32_e32 v52, v52, v53
	v_exp_f32_e32 v50, v52
	v_cvt_i32_f32_e32 v54, v54
	v_cmp_nlt_f32_e32 vcc, 0x42ce8ed0, v46
	v_ldexp_f32 v50, v50, v54
	s_nop 0
	v_cndmask_b32_e32 v50, 0, v50, vcc
	v_cmp_ngt_f32_e32 vcc, 0xc2b17218, v46
	s_nop 1
	v_cndmask_b32_e32 v50, v192, v50, vcc
	v_mul_f32_e32 v52, 0xbfb8aa3b, v47
	v_fma_f32 v53, v47, s20, -v52
	v_rndne_f32_e32 v54, v52
	v_fmac_f32_e32 v53, 0xb2a5705f, v47
	v_sub_f32_e32 v52, v52, v54
	v_add_f32_e32 v52, v52, v53
	v_exp_f32_e32 v51, v52
	v_cvt_i32_f32_e32 v54, v54
	v_cmp_nlt_f32_e32 vcc, 0x42ce8ed0, v47
	v_ldexp_f32 v51, v51, v54
	s_nop 0
	v_cndmask_b32_e32 v51, 0, v51, vcc
	v_cmp_ngt_f32_e32 vcc, 0xc2b17218, v47
	s_nop 1
	v_cndmask_b32_e32 v51, v192, v51, vcc
	v_pk_add_f32 v[48:49], v[48:49], 1.0 op_sel_hi:[1,0]
	v_pk_add_f32 v[50:51], v[50:51], 1.0 op_sel_hi:[1,0]
	v_div_scale_f32 v52, s[2:3], v48, v48, v44
	v_rcp_f32_e32 v53, v52
	s_nop 0
	v_fma_f32 v54, -v52, v53, 1.0
	v_fmac_f32_e32 v53, v54, v53
	v_div_scale_f32 v54, vcc, v44, v48, v44
	v_mul_f32_e32 v55, v54, v53
	v_fma_f32 v40, -v52, v55, v54
	v_fmac_f32_e32 v55, v40, v53
	v_fma_f32 v52, -v52, v55, v54
	v_div_fmas_f32 v52, v52, v53, v55
	v_div_fixup_f32 v40, v52, v48, v44
	v_div_scale_f32 v52, s[2:3], v49, v49, v45
	v_rcp_f32_e32 v53, v52
	s_nop 0
	v_fma_f32 v54, -v52, v53, 1.0
	v_fmac_f32_e32 v53, v54, v53
	v_div_scale_f32 v54, vcc, v45, v49, v45
	v_mul_f32_e32 v55, v54, v53
	v_fma_f32 v41, -v52, v55, v54
	v_fmac_f32_e32 v55, v41, v53
	v_fma_f32 v52, -v52, v55, v54
	v_div_fmas_f32 v52, v52, v53, v55
	v_div_fixup_f32 v41, v52, v49, v45
	v_div_scale_f32 v52, s[2:3], v50, v50, v46
	v_rcp_f32_e32 v53, v52
	s_nop 0
	v_fma_f32 v54, -v52, v53, 1.0
	v_fmac_f32_e32 v53, v54, v53
	v_div_scale_f32 v54, vcc, v46, v50, v46
	v_mul_f32_e32 v55, v54, v53
	v_fma_f32 v42, -v52, v55, v54
	v_fmac_f32_e32 v55, v42, v53
	v_fma_f32 v52, -v52, v55, v54
	v_div_fmas_f32 v52, v52, v53, v55
	v_div_fixup_f32 v42, v52, v50, v46
	v_div_scale_f32 v52, s[2:3], v51, v51, v47
	v_rcp_f32_e32 v53, v52
	s_nop 0
	v_fma_f32 v54, -v52, v53, 1.0
	v_fmac_f32_e32 v53, v54, v53
	v_div_scale_f32 v54, vcc, v47, v51, v47
	v_mul_f32_e32 v55, v54, v53
	v_fma_f32 v43, -v52, v55, v54
	v_fmac_f32_e32 v55, v43, v53
	v_fma_f32 v52, -v52, v55, v54
	v_div_fmas_f32 v52, v52, v53, v55
	v_div_fixup_f32 v43, v52, v51, v47
	v_fmamk_f32 v34, v34, 0x3b800000, v177
	v_mul_f32_e32 v35, 0x4b800000, v34
	v_cmp_gt_f32_e32 vcc, 0x800000, v34
	s_nop 1
	v_cndmask_b32_e32 v34, v34, v35, vcc
	v_rsq_f32_e32 v38, v34
	s_nop 0
	v_mul_f32_e32 v35, 0x45800000, v38
	v_cndmask_b32_e32 v38, v38, v35, vcc
	v_pk_mul_f32 v[32:33], v[32:33], v[38:39] op_sel_hi:[1,0]
	v_pk_mul_f32 v[36:37], v[36:37], v[38:39] op_sel_hi:[1,0]
	v_pk_mul_f32 v[32:33], v[0:1], v[32:33]
	v_pk_mul_f32 v[36:37], v[2:3], v[36:37]
	v_pk_mul_f32 v[32:33], v[40:41], v[32:33]
	v_pk_mul_f32 v[36:37], v[42:43], v[36:37]
	v_cvt_pk_bf16_f32 v56, v32, v33
	v_cvt_pk_bf16_f32 v57, v36, v37
	s_mov_b32 s0, 0
	s_lshl_b32 s1, s0, 20
	s_add_u32 s16, s14, s1
	s_addc_u32 s17, s15, 0
	global_store_dwordx2 v4, v[56:57], s[16:17]
	s_waitcnt vmcnt(10)
	v_lshlrev_b32_e32 v32, 16, v14
	v_and_b32_e32 v33, 0xffff0000, v14
	v_lshlrev_b32_e32 v34, 16, v16
	v_and_b32_e32 v35, 0xffff0000, v16
	v_lshlrev_b32_e32 v36, 16, v15
	v_and_b32_e32 v37, 0xffff0000, v15
	v_lshlrev_b32_e32 v38, 16, v17
	v_and_b32_e32 v39, 0xffff0000, v17
	v_pk_add_f32 v[32:33], v[32:33], v[34:35]
	v_pk_add_f32 v[36:37], v[36:37], v[38:39]
	v_lshlrev_b32_e32 v44, 16, v18
	v_and_b32_e32 v45, 0xffff0000, v18
	v_lshlrev_b32_e32 v46, 16, v19
	v_and_b32_e32 v47, 0xffff0000, v19
	s_mov_b32 s0, 5
	s_lshl_b32 s1, s0, 20
	s_add_u32 s16, s6, s1
	s_addc_u32 s17, s7, 0
	s_add_u32 s18, s8, s1
	s_addc_u32 s19, s9, 0
	s_mul_i32 s1, s0, 0x300000
	s_add_u32 s12, s10, s1
	s_addc_u32 s13, s11, 0
	global_load_dwordx2 v[14:15], v4, s[16:17] nt
	global_load_dwordx2 v[16:17], v4, s[18:19] nt
	global_load_dwordx2 v[18:19], v4, s[12:13] nt
	v_pk_mul_f32 v[34:35], v[32:33], v[32:33]
	v_pk_mul_f32 v[38:39], v[36:37], v[36:37]
	v_add_f32_e32 v34, v34, v35
	v_add_f32_e32 v34, v34, v38
	v_add_f32_e32 v34, v34, v39
	s_nop 1
	v_add_f32_dpp v34, v34, v34 row_ror:8 row_mask:0xf bank_mask:0xf
	s_nop 1
	v_add_f32_dpp v34, v34, v34 row_ror:4 row_mask:0xf bank_mask:0xf
	s_nop 1
	v_add_f32_dpp v34, v34, v34 row_ror:2 row_mask:0xf bank_mask:0xf
	s_nop 1
	v_add_f32_dpp v34, v34, v34 row_ror:1 row_mask:0xf bank_mask:0xf
	v_mov_b32_e32 v35, v34
	s_nop 1
	v_permlane16_swap_b32 v34, v35
	v_add_f32_e32 v34, v34, v35
	v_mov_b32_e32 v35, v34
	s_nop 1
	v_permlane32_swap_b32 v34, v35
	v_add_f32_e32 v34, v34, v35
	v_mul_f32_e32 v52, 0xbfb8aa3b, v44
	v_fma_f32 v53, v44, s20, -v52
	v_rndne_f32_e32 v54, v52
	v_fmac_f32_e32 v53, 0xb2a5705f, v44
	v_sub_f32_e32 v52, v52, v54
	v_add_f32_e32 v52, v52, v53
	v_exp_f32_e32 v48, v52
	v_cvt_i32_f32_e32 v54, v54
	v_cmp_nlt_f32_e32 vcc, 0x42ce8ed0, v44
	v_ldexp_f32 v48, v48, v54
	s_nop 0
	v_cndmask_b32_e32 v48, 0, v48, vcc
	v_cmp_ngt_f32_e32 vcc, 0xc2b17218, v44
	s_nop 1
	v_cndmask_b32_e32 v48, v192, v48, vcc
	v_mul_f32_e32 v52, 0xbfb8aa3b, v45
	v_fma_f32 v53, v45, s20, -v52
	v_rndne_f32_e32 v54, v52
	v_fmac_f32_e32 v53, 0xb2a5705f, v45
	v_sub_f32_e32 v52, v52, v54
	v_add_f32_e32 v52, v52, v53
	v_exp_f32_e32 v49, v52
	v_cvt_i32_f32_e32 v54, v54
	v_cmp_nlt_f32_e32 vcc, 0x42ce8ed0, v45
	v_ldexp_f32 v49, v49, v54
	s_nop 0
	v_cndmask_b32_e32 v49, 0, v49, vcc
	v_cmp_ngt_f32_e32 vcc, 0xc2b17218, v45
	s_nop 1
	v_cndmask_b32_e32 v49, v192, v49, vcc
	v_mul_f32_e32 v52, 0xbfb8aa3b, v46
	v_fma_f32 v53, v46, s20, -v52
	v_rndne_f32_e32 v54, v52
	v_fmac_f32_e32 v53, 0xb2a5705f, v46
	v_sub_f32_e32 v52, v52, v54
	v_add_f32_e32 v52, v52, v53
	v_exp_f32_e32 v50, v52
	v_cvt_i32_f32_e32 v54, v54
	v_cmp_nlt_f32_e32 vcc, 0x42ce8ed0, v46
	v_ldexp_f32 v50, v50, v54
	s_nop 0
	v_cndmask_b32_e32 v50, 0, v50, vcc
	v_cmp_ngt_f32_e32 vcc, 0xc2b17218, v46
	s_nop 1
	v_cndmask_b32_e32 v50, v192, v50, vcc
	v_mul_f32_e32 v52, 0xbfb8aa3b, v47
	v_fma_f32 v53, v47, s20, -v52
	v_rndne_f32_e32 v54, v52
	v_fmac_f32_e32 v53, 0xb2a5705f, v47
	v_sub_f32_e32 v52, v52, v54
	v_add_f32_e32 v52, v52, v53
	v_exp_f32_e32 v51, v52
	v_cvt_i32_f32_e32 v54, v54
	v_cmp_nlt_f32_e32 vcc, 0x42ce8ed0, v47
	v_ldexp_f32 v51, v51, v54
	s_nop 0
	v_cndmask_b32_e32 v51, 0, v51, vcc
	v_cmp_ngt_f32_e32 vcc, 0xc2b17218, v47
	s_nop 1
	v_cndmask_b32_e32 v51, v192, v51, vcc
	v_pk_add_f32 v[48:49], v[48:49], 1.0 op_sel_hi:[1,0]
	v_pk_add_f32 v[50:51], v[50:51], 1.0 op_sel_hi:[1,0]
	v_div_scale_f32 v52, s[2:3], v48, v48, v44
	v_rcp_f32_e32 v53, v52
	s_nop 0
	v_fma_f32 v54, -v52, v53, 1.0
	v_fmac_f32_e32 v53, v54, v53
	v_div_scale_f32 v54, vcc, v44, v48, v44
	v_mul_f32_e32 v55, v54, v53
	v_fma_f32 v40, -v52, v55, v54
	v_fmac_f32_e32 v55, v40, v53
	v_fma_f32 v52, -v52, v55, v54
	v_div_fmas_f32 v52, v52, v53, v55
	v_div_fixup_f32 v40, v52, v48, v44
	v_div_scale_f32 v52, s[2:3], v49, v49, v45
	v_rcp_f32_e32 v53, v52
	s_nop 0
	v_fma_f32 v54, -v52, v53, 1.0
	v_fmac_f32_e32 v53, v54, v53
	v_div_scale_f32 v54, vcc, v45, v49, v45
	v_mul_f32_e32 v55, v54, v53
	v_fma_f32 v41, -v52, v55, v54
	v_fmac_f32_e32 v55, v41, v53
	v_fma_f32 v52, -v52, v55, v54
	v_div_fmas_f32 v52, v52, v53, v55
	v_div_fixup_f32 v41, v52, v49, v45
	v_div_scale_f32 v52, s[2:3], v50, v50, v46
	v_rcp_f32_e32 v53, v52
	s_nop 0
	v_fma_f32 v54, -v52, v53, 1.0
	v_fmac_f32_e32 v53, v54, v53
	v_div_scale_f32 v54, vcc, v46, v50, v46
	v_mul_f32_e32 v55, v54, v53
	v_fma_f32 v42, -v52, v55, v54
	v_fmac_f32_e32 v55, v42, v53
	v_fma_f32 v52, -v52, v55, v54
	v_div_fmas_f32 v52, v52, v53, v55
	v_div_fixup_f32 v42, v52, v50, v46
	v_div_scale_f32 v52, s[2:3], v51, v51, v47
	v_rcp_f32_e32 v53, v52
	s_nop 0
	v_fma_f32 v54, -v52, v53, 1.0
	v_fmac_f32_e32 v53, v54, v53
	v_div_scale_f32 v54, vcc, v47, v51, v47
	v_mul_f32_e32 v55, v54, v53
	v_fma_f32 v43, -v52, v55, v54
	v_fmac_f32_e32 v55, v43, v53
	v_fma_f32 v52, -v52, v55, v54
	v_div_fmas_f32 v52, v52, v53, v55
	v_div_fixup_f32 v43, v52, v51, v47
	v_fmamk_f32 v34, v34, 0x3b800000, v177
	v_mul_f32_e32 v35, 0x4b800000, v34
	v_cmp_gt_f32_e32 vcc, 0x800000, v34
	s_nop 1
	v_cndmask_b32_e32 v34, v34, v35, vcc
	v_rsq_f32_e32 v38, v34
	s_nop 0
	v_mul_f32_e32 v35, 0x45800000, v38
	v_cndmask_b32_e32 v38, v38, v35, vcc
	v_pk_mul_f32 v[32:33], v[32:33], v[38:39] op_sel_hi:[1,0]
	v_pk_mul_f32 v[36:37], v[36:37], v[38:39] op_sel_hi:[1,0]
	v_pk_mul_f32 v[32:33], v[0:1], v[32:33]
	v_pk_mul_f32 v[36:37], v[2:3], v[36:37]
	v_pk_mul_f32 v[32:33], v[40:41], v[32:33]
	v_pk_mul_f32 v[36:37], v[42:43], v[36:37]
	v_cvt_pk_bf16_f32 v56, v32, v33
	v_cvt_pk_bf16_f32 v57, v36, v37
	s_mov_b32 s0, 1
	s_lshl_b32 s1, s0, 20
	s_add_u32 s16, s14, s1
	s_addc_u32 s17, s15, 0
	global_store_dwordx2 v4, v[56:57], s[16:17]
	s_waitcnt vmcnt(11)
	v_lshlrev_b32_e32 v32, 16, v20
	v_and_b32_e32 v33, 0xffff0000, v20
	v_lshlrev_b32_e32 v34, 16, v22
	v_and_b32_e32 v35, 0xffff0000, v22
	v_lshlrev_b32_e32 v36, 16, v21
	v_and_b32_e32 v37, 0xffff0000, v21
	v_lshlrev_b32_e32 v38, 16, v23
	v_and_b32_e32 v39, 0xffff0000, v23
	v_pk_add_f32 v[32:33], v[32:33], v[34:35]
	v_pk_add_f32 v[36:37], v[36:37], v[38:39]
	v_lshlrev_b32_e32 v44, 16, v24
	v_and_b32_e32 v45, 0xffff0000, v24
	v_lshlrev_b32_e32 v46, 16, v25
	v_and_b32_e32 v47, 0xffff0000, v25
	s_mov_b32 s0, 6
	s_lshl_b32 s1, s0, 20
	s_add_u32 s16, s6, s1
	s_addc_u32 s17, s7, 0
	s_add_u32 s18, s8, s1
	s_addc_u32 s19, s9, 0
	s_mul_i32 s1, s0, 0x300000
	s_add_u32 s12, s10, s1
	s_addc_u32 s13, s11, 0
	global_load_dwordx2 v[20:21], v4, s[16:17] nt
	global_load_dwordx2 v[22:23], v4, s[18:19] nt
	global_load_dwordx2 v[24:25], v4, s[12:13] nt
	v_pk_mul_f32 v[34:35], v[32:33], v[32:33]
	v_pk_mul_f32 v[38:39], v[36:37], v[36:37]
	v_add_f32_e32 v34, v34, v35
	v_add_f32_e32 v34, v34, v38
	v_add_f32_e32 v34, v34, v39
	s_nop 1
	v_add_f32_dpp v34, v34, v34 row_ror:8 row_mask:0xf bank_mask:0xf
	s_nop 1
	v_add_f32_dpp v34, v34, v34 row_ror:4 row_mask:0xf bank_mask:0xf
	s_nop 1
	v_add_f32_dpp v34, v34, v34 row_ror:2 row_mask:0xf bank_mask:0xf
	s_nop 1
	v_add_f32_dpp v34, v34, v34 row_ror:1 row_mask:0xf bank_mask:0xf
	v_mov_b32_e32 v35, v34
	s_nop 1
	v_permlane16_swap_b32 v34, v35
	v_add_f32_e32 v34, v34, v35
	v_mov_b32_e32 v35, v34
	s_nop 1
	v_permlane32_swap_b32 v34, v35
	v_add_f32_e32 v34, v34, v35
	v_mul_f32_e32 v52, 0xbfb8aa3b, v44
	v_fma_f32 v53, v44, s20, -v52
	v_rndne_f32_e32 v54, v52
	v_fmac_f32_e32 v53, 0xb2a5705f, v44
	v_sub_f32_e32 v52, v52, v54
	v_add_f32_e32 v52, v52, v53
	v_exp_f32_e32 v48, v52
	v_cvt_i32_f32_e32 v54, v54
	v_cmp_nlt_f32_e32 vcc, 0x42ce8ed0, v44
	v_ldexp_f32 v48, v48, v54
	s_nop 0
	v_cndmask_b32_e32 v48, 0, v48, vcc
	v_cmp_ngt_f32_e32 vcc, 0xc2b17218, v44
	s_nop 1
	v_cndmask_b32_e32 v48, v192, v48, vcc
	v_mul_f32_e32 v52, 0xbfb8aa3b, v45
	v_fma_f32 v53, v45, s20, -v52
	v_rndne_f32_e32 v54, v52
	v_fmac_f32_e32 v53, 0xb2a5705f, v45
	v_sub_f32_e32 v52, v52, v54
	v_add_f32_e32 v52, v52, v53
	v_exp_f32_e32 v49, v52
	v_cvt_i32_f32_e32 v54, v54
	v_cmp_nlt_f32_e32 vcc, 0x42ce8ed0, v45
	v_ldexp_f32 v49, v49, v54
	s_nop 0
	v_cndmask_b32_e32 v49, 0, v49, vcc
	v_cmp_ngt_f32_e32 vcc, 0xc2b17218, v45
	s_nop 1
	v_cndmask_b32_e32 v49, v192, v49, vcc
	v_mul_f32_e32 v52, 0xbfb8aa3b, v46
	v_fma_f32 v53, v46, s20, -v52
	v_rndne_f32_e32 v54, v52
	v_fmac_f32_e32 v53, 0xb2a5705f, v46
	v_sub_f32_e32 v52, v52, v54
	v_add_f32_e32 v52, v52, v53
	v_exp_f32_e32 v50, v52
	v_cvt_i32_f32_e32 v54, v54
	v_cmp_nlt_f32_e32 vcc, 0x42ce8ed0, v46
	v_ldexp_f32 v50, v50, v54
	s_nop 0
	v_cndmask_b32_e32 v50, 0, v50, vcc
	v_cmp_ngt_f32_e32 vcc, 0xc2b17218, v46
	s_nop 1
	v_cndmask_b32_e32 v50, v192, v50, vcc
	v_mul_f32_e32 v52, 0xbfb8aa3b, v47
	v_fma_f32 v53, v47, s20, -v52
	v_rndne_f32_e32 v54, v52
	v_fmac_f32_e32 v53, 0xb2a5705f, v47
	v_sub_f32_e32 v52, v52, v54
	v_add_f32_e32 v52, v52, v53
	v_exp_f32_e32 v51, v52
	v_cvt_i32_f32_e32 v54, v54
	v_cmp_nlt_f32_e32 vcc, 0x42ce8ed0, v47
	v_ldexp_f32 v51, v51, v54
	s_nop 0
	v_cndmask_b32_e32 v51, 0, v51, vcc
	v_cmp_ngt_f32_e32 vcc, 0xc2b17218, v47
	s_nop 1
	v_cndmask_b32_e32 v51, v192, v51, vcc
	v_pk_add_f32 v[48:49], v[48:49], 1.0 op_sel_hi:[1,0]
	v_pk_add_f32 v[50:51], v[50:51], 1.0 op_sel_hi:[1,0]
	v_div_scale_f32 v52, s[2:3], v48, v48, v44
	v_rcp_f32_e32 v53, v52
	s_nop 0
	v_fma_f32 v54, -v52, v53, 1.0
	v_fmac_f32_e32 v53, v54, v53
	v_div_scale_f32 v54, vcc, v44, v48, v44
	v_mul_f32_e32 v55, v54, v53
	v_fma_f32 v40, -v52, v55, v54
	v_fmac_f32_e32 v55, v40, v53
	v_fma_f32 v52, -v52, v55, v54
	v_div_fmas_f32 v52, v52, v53, v55
	v_div_fixup_f32 v40, v52, v48, v44
	v_div_scale_f32 v52, s[2:3], v49, v49, v45
	v_rcp_f32_e32 v53, v52
	s_nop 0
	v_fma_f32 v54, -v52, v53, 1.0
	v_fmac_f32_e32 v53, v54, v53
	v_div_scale_f32 v54, vcc, v45, v49, v45
	v_mul_f32_e32 v55, v54, v53
	v_fma_f32 v41, -v52, v55, v54
	v_fmac_f32_e32 v55, v41, v53
	v_fma_f32 v52, -v52, v55, v54
	v_div_fmas_f32 v52, v52, v53, v55
	v_div_fixup_f32 v41, v52, v49, v45
	v_div_scale_f32 v52, s[2:3], v50, v50, v46
	v_rcp_f32_e32 v53, v52
	s_nop 0
	v_fma_f32 v54, -v52, v53, 1.0
	v_fmac_f32_e32 v53, v54, v53
	v_div_scale_f32 v54, vcc, v46, v50, v46
	v_mul_f32_e32 v55, v54, v53
	v_fma_f32 v42, -v52, v55, v54
	v_fmac_f32_e32 v55, v42, v53
	v_fma_f32 v52, -v52, v55, v54
	v_div_fmas_f32 v52, v52, v53, v55
	v_div_fixup_f32 v42, v52, v50, v46
	v_div_scale_f32 v52, s[2:3], v51, v51, v47
	v_rcp_f32_e32 v53, v52
	s_nop 0
	v_fma_f32 v54, -v52, v53, 1.0
	v_fmac_f32_e32 v53, v54, v53
	v_div_scale_f32 v54, vcc, v47, v51, v47
	v_mul_f32_e32 v55, v54, v53
	v_fma_f32 v43, -v52, v55, v54
	v_fmac_f32_e32 v55, v43, v53
	v_fma_f32 v52, -v52, v55, v54
	v_div_fmas_f32 v52, v52, v53, v55
	v_div_fixup_f32 v43, v52, v51, v47
	v_fmamk_f32 v34, v34, 0x3b800000, v177
	v_mul_f32_e32 v35, 0x4b800000, v34
	v_cmp_gt_f32_e32 vcc, 0x800000, v34
	s_nop 1
	v_cndmask_b32_e32 v34, v34, v35, vcc
	v_rsq_f32_e32 v38, v34
	s_nop 0
	v_mul_f32_e32 v35, 0x45800000, v38
	v_cndmask_b32_e32 v38, v38, v35, vcc
	v_pk_mul_f32 v[32:33], v[32:33], v[38:39] op_sel_hi:[1,0]
	v_pk_mul_f32 v[36:37], v[36:37], v[38:39] op_sel_hi:[1,0]
	v_pk_mul_f32 v[32:33], v[0:1], v[32:33]
	v_pk_mul_f32 v[36:37], v[2:3], v[36:37]
	v_pk_mul_f32 v[32:33], v[40:41], v[32:33]
	v_pk_mul_f32 v[36:37], v[42:43], v[36:37]
	v_cvt_pk_bf16_f32 v56, v32, v33
	v_cvt_pk_bf16_f32 v57, v36, v37
	s_mov_b32 s0, 2
	s_lshl_b32 s1, s0, 20
	s_add_u32 s16, s14, s1
	s_addc_u32 s17, s15, 0
	global_store_dwordx2 v4, v[56:57], s[16:17]
	s_waitcnt vmcnt(12)
	v_lshlrev_b32_e32 v32, 16, v26
	v_and_b32_e32 v33, 0xffff0000, v26
	v_lshlrev_b32_e32 v34, 16, v28
	v_and_b32_e32 v35, 0xffff0000, v28
	v_lshlrev_b32_e32 v36, 16, v27
	v_and_b32_e32 v37, 0xffff0000, v27
	v_lshlrev_b32_e32 v38, 16, v29
	v_and_b32_e32 v39, 0xffff0000, v29
	v_pk_add_f32 v[32:33], v[32:33], v[34:35]
	v_pk_add_f32 v[36:37], v[36:37], v[38:39]
	v_lshlrev_b32_e32 v44, 16, v30
	v_and_b32_e32 v45, 0xffff0000, v30
	v_lshlrev_b32_e32 v46, 16, v31
	v_and_b32_e32 v47, 0xffff0000, v31
	s_mov_b32 s0, 7
	s_lshl_b32 s1, s0, 20
	s_add_u32 s16, s6, s1
	s_addc_u32 s17, s7, 0
	s_add_u32 s18, s8, s1
	s_addc_u32 s19, s9, 0
	s_mul_i32 s1, s0, 0x300000
	s_add_u32 s12, s10, s1
	s_addc_u32 s13, s11, 0
	global_load_dwordx2 v[26:27], v4, s[16:17] nt
	global_load_dwordx2 v[28:29], v4, s[18:19] nt
	global_load_dwordx2 v[30:31], v4, s[12:13] nt
	v_pk_mul_f32 v[34:35], v[32:33], v[32:33]
	v_pk_mul_f32 v[38:39], v[36:37], v[36:37]
	v_add_f32_e32 v34, v34, v35
	v_add_f32_e32 v34, v34, v38
	v_add_f32_e32 v34, v34, v39
	s_nop 1
	v_add_f32_dpp v34, v34, v34 row_ror:8 row_mask:0xf bank_mask:0xf
	s_nop 1
	v_add_f32_dpp v34, v34, v34 row_ror:4 row_mask:0xf bank_mask:0xf
	s_nop 1
	v_add_f32_dpp v34, v34, v34 row_ror:2 row_mask:0xf bank_mask:0xf
	s_nop 1
	v_add_f32_dpp v34, v34, v34 row_ror:1 row_mask:0xf bank_mask:0xf
	v_mov_b32_e32 v35, v34
	s_nop 1
	v_permlane16_swap_b32 v34, v35
	v_add_f32_e32 v34, v34, v35
	v_mov_b32_e32 v35, v34
	s_nop 1
	v_permlane32_swap_b32 v34, v35
	v_add_f32_e32 v34, v34, v35
	v_mul_f32_e32 v52, 0xbfb8aa3b, v44
	v_fma_f32 v53, v44, s20, -v52
	v_rndne_f32_e32 v54, v52
	v_fmac_f32_e32 v53, 0xb2a5705f, v44
	v_sub_f32_e32 v52, v52, v54
	v_add_f32_e32 v52, v52, v53
	v_exp_f32_e32 v48, v52
	v_cvt_i32_f32_e32 v54, v54
	v_cmp_nlt_f32_e32 vcc, 0x42ce8ed0, v44
	v_ldexp_f32 v48, v48, v54
	s_nop 0
	v_cndmask_b32_e32 v48, 0, v48, vcc
	v_cmp_ngt_f32_e32 vcc, 0xc2b17218, v44
	s_nop 1
	v_cndmask_b32_e32 v48, v192, v48, vcc
	v_mul_f32_e32 v52, 0xbfb8aa3b, v45
	v_fma_f32 v53, v45, s20, -v52
	v_rndne_f32_e32 v54, v52
	v_fmac_f32_e32 v53, 0xb2a5705f, v45
	v_sub_f32_e32 v52, v52, v54
	v_add_f32_e32 v52, v52, v53
	v_exp_f32_e32 v49, v52
	v_cvt_i32_f32_e32 v54, v54
	v_cmp_nlt_f32_e32 vcc, 0x42ce8ed0, v45
	v_ldexp_f32 v49, v49, v54
	s_nop 0
	v_cndmask_b32_e32 v49, 0, v49, vcc
	v_cmp_ngt_f32_e32 vcc, 0xc2b17218, v45
	s_nop 1
	v_cndmask_b32_e32 v49, v192, v49, vcc
	v_mul_f32_e32 v52, 0xbfb8aa3b, v46
	v_fma_f32 v53, v46, s20, -v52
	v_rndne_f32_e32 v54, v52
	v_fmac_f32_e32 v53, 0xb2a5705f, v46
	v_sub_f32_e32 v52, v52, v54
	v_add_f32_e32 v52, v52, v53
	v_exp_f32_e32 v50, v52
	v_cvt_i32_f32_e32 v54, v54
	v_cmp_nlt_f32_e32 vcc, 0x42ce8ed0, v46
	v_ldexp_f32 v50, v50, v54
	s_nop 0
	v_cndmask_b32_e32 v50, 0, v50, vcc
	v_cmp_ngt_f32_e32 vcc, 0xc2b17218, v46
	s_nop 1
	v_cndmask_b32_e32 v50, v192, v50, vcc
	v_mul_f32_e32 v52, 0xbfb8aa3b, v47
	v_fma_f32 v53, v47, s20, -v52
	v_rndne_f32_e32 v54, v52
	v_fmac_f32_e32 v53, 0xb2a5705f, v47
	v_sub_f32_e32 v52, v52, v54
	v_add_f32_e32 v52, v52, v53
	v_exp_f32_e32 v51, v52
	v_cvt_i32_f32_e32 v54, v54
	v_cmp_nlt_f32_e32 vcc, 0x42ce8ed0, v47
	v_ldexp_f32 v51, v51, v54
	s_nop 0
	v_cndmask_b32_e32 v51, 0, v51, vcc
	v_cmp_ngt_f32_e32 vcc, 0xc2b17218, v47
	s_nop 1
	v_cndmask_b32_e32 v51, v192, v51, vcc
	v_pk_add_f32 v[48:49], v[48:49], 1.0 op_sel_hi:[1,0]
	v_pk_add_f32 v[50:51], v[50:51], 1.0 op_sel_hi:[1,0]
	v_div_scale_f32 v52, s[2:3], v48, v48, v44
	v_rcp_f32_e32 v53, v52
	s_nop 0
	v_fma_f32 v54, -v52, v53, 1.0
	v_fmac_f32_e32 v53, v54, v53
	v_div_scale_f32 v54, vcc, v44, v48, v44
	v_mul_f32_e32 v55, v54, v53
	v_fma_f32 v40, -v52, v55, v54
	v_fmac_f32_e32 v55, v40, v53
	v_fma_f32 v52, -v52, v55, v54
	v_div_fmas_f32 v52, v52, v53, v55
	v_div_fixup_f32 v40, v52, v48, v44
	v_div_scale_f32 v52, s[2:3], v49, v49, v45
	v_rcp_f32_e32 v53, v52
	s_nop 0
	v_fma_f32 v54, -v52, v53, 1.0
	v_fmac_f32_e32 v53, v54, v53
	v_div_scale_f32 v54, vcc, v45, v49, v45
	v_mul_f32_e32 v55, v54, v53
	v_fma_f32 v41, -v52, v55, v54
	v_fmac_f32_e32 v55, v41, v53
	v_fma_f32 v52, -v52, v55, v54
	v_div_fmas_f32 v52, v52, v53, v55
	v_div_fixup_f32 v41, v52, v49, v45
	v_div_scale_f32 v52, s[2:3], v50, v50, v46
	v_rcp_f32_e32 v53, v52
	s_nop 0
	v_fma_f32 v54, -v52, v53, 1.0
	v_fmac_f32_e32 v53, v54, v53
	v_div_scale_f32 v54, vcc, v46, v50, v46
	v_mul_f32_e32 v55, v54, v53
	v_fma_f32 v42, -v52, v55, v54
	v_fmac_f32_e32 v55, v42, v53
	v_fma_f32 v52, -v52, v55, v54
	v_div_fmas_f32 v52, v52, v53, v55
	v_div_fixup_f32 v42, v52, v50, v46
	v_div_scale_f32 v52, s[2:3], v51, v51, v47
	v_rcp_f32_e32 v53, v52
	s_nop 0
	v_fma_f32 v54, -v52, v53, 1.0
	v_fmac_f32_e32 v53, v54, v53
	v_div_scale_f32 v54, vcc, v47, v51, v47
	v_mul_f32_e32 v55, v54, v53
	v_fma_f32 v43, -v52, v55, v54
	v_fmac_f32_e32 v55, v43, v53
	v_fma_f32 v52, -v52, v55, v54
	v_div_fmas_f32 v52, v52, v53, v55
	v_div_fixup_f32 v43, v52, v51, v47
	v_fmamk_f32 v34, v34, 0x3b800000, v177
	v_mul_f32_e32 v35, 0x4b800000, v34
	v_cmp_gt_f32_e32 vcc, 0x800000, v34
	s_nop 1
	v_cndmask_b32_e32 v34, v34, v35, vcc
	v_rsq_f32_e32 v38, v34
	s_nop 0
	v_mul_f32_e32 v35, 0x45800000, v38
	v_cndmask_b32_e32 v38, v38, v35, vcc
	v_pk_mul_f32 v[32:33], v[32:33], v[38:39] op_sel_hi:[1,0]
	v_pk_mul_f32 v[36:37], v[36:37], v[38:39] op_sel_hi:[1,0]
	v_pk_mul_f32 v[32:33], v[0:1], v[32:33]
	v_pk_mul_f32 v[36:37], v[2:3], v[36:37]
	v_pk_mul_f32 v[32:33], v[40:41], v[32:33]
	v_pk_mul_f32 v[36:37], v[42:43], v[36:37]
	v_cvt_pk_bf16_f32 v56, v32, v33
	v_cvt_pk_bf16_f32 v57, v36, v37
	s_mov_b32 s0, 3
	s_lshl_b32 s1, s0, 20
	s_add_u32 s16, s14, s1
	s_addc_u32 s17, s15, 0
	global_store_dwordx2 v4, v[56:57], s[16:17]
	s_mov_b32 s21, 1
.Lcomb_loop:
	s_waitcnt vmcnt(13)
	v_lshlrev_b32_e32 v32, 16, v8
	v_and_b32_e32 v33, 0xffff0000, v8
	v_lshlrev_b32_e32 v34, 16, v10
	v_and_b32_e32 v35, 0xffff0000, v10
	v_lshlrev_b32_e32 v36, 16, v9
	v_and_b32_e32 v37, 0xffff0000, v9
	v_lshlrev_b32_e32 v38, 16, v11
	v_and_b32_e32 v39, 0xffff0000, v11
	v_pk_add_f32 v[32:33], v[32:33], v[34:35]
	v_pk_add_f32 v[36:37], v[36:37], v[38:39]
	v_lshlrev_b32_e32 v44, 16, v12
	v_and_b32_e32 v45, 0xffff0000, v12
	v_lshlrev_b32_e32 v46, 16, v13
	v_and_b32_e32 v47, 0xffff0000, v13
	s_lshl_b32 s0, s21, 2
	s_add_i32 s0, s0, 4
	s_min_u32 s0, s0, 23
	s_lshl_b32 s1, s0, 20
	s_add_u32 s16, s6, s1
	s_addc_u32 s17, s7, 0
	s_add_u32 s18, s8, s1
	s_addc_u32 s19, s9, 0
	s_mul_i32 s1, s0, 0x300000
	s_add_u32 s12, s10, s1
	s_addc_u32 s13, s11, 0
	global_load_dwordx2 v[8:9], v4, s[16:17] nt
	global_load_dwordx2 v[10:11], v4, s[18:19] nt
	global_load_dwordx2 v[12:13], v4, s[12:13] nt
	v_pk_mul_f32 v[34:35], v[32:33], v[32:33]
	v_pk_mul_f32 v[38:39], v[36:37], v[36:37]
	v_add_f32_e32 v34, v34, v35
	v_add_f32_e32 v34, v34, v38
	v_add_f32_e32 v34, v34, v39
	s_nop 1
	v_add_f32_dpp v34, v34, v34 row_ror:8 row_mask:0xf bank_mask:0xf
	s_nop 1
	v_add_f32_dpp v34, v34, v34 row_ror:4 row_mask:0xf bank_mask:0xf
	s_nop 1
	v_add_f32_dpp v34, v34, v34 row_ror:2 row_mask:0xf bank_mask:0xf
	s_nop 1
	v_add_f32_dpp v34, v34, v34 row_ror:1 row_mask:0xf bank_mask:0xf
	v_mov_b32_e32 v35, v34
	s_nop 1
	v_permlane16_swap_b32 v34, v35
	v_add_f32_e32 v34, v34, v35
	v_mov_b32_e32 v35, v34
	s_nop 1
	v_permlane32_swap_b32 v34, v35
	v_add_f32_e32 v34, v34, v35
	v_mul_f32_e32 v52, 0xbfb8aa3b, v44
	v_fma_f32 v53, v44, s20, -v52
	v_rndne_f32_e32 v54, v52
	v_fmac_f32_e32 v53, 0xb2a5705f, v44
	v_sub_f32_e32 v52, v52, v54
	v_add_f32_e32 v52, v52, v53
	v_exp_f32_e32 v48, v52
	v_cvt_i32_f32_e32 v54, v54
	v_cmp_nlt_f32_e32 vcc, 0x42ce8ed0, v44
	v_ldexp_f32 v48, v48, v54
	s_nop 0
	v_cndmask_b32_e32 v48, 0, v48, vcc
	v_cmp_ngt_f32_e32 vcc, 0xc2b17218, v44
	s_nop 1
	v_cndmask_b32_e32 v48, v192, v48, vcc
	v_mul_f32_e32 v52, 0xbfb8aa3b, v45
	v_fma_f32 v53, v45, s20, -v52
	v_rndne_f32_e32 v54, v52
	v_fmac_f32_e32 v53, 0xb2a5705f, v45
	v_sub_f32_e32 v52, v52, v54
	v_add_f32_e32 v52, v52, v53
	v_exp_f32_e32 v49, v52
	v_cvt_i32_f32_e32 v54, v54
	v_cmp_nlt_f32_e32 vcc, 0x42ce8ed0, v45
	v_ldexp_f32 v49, v49, v54
	s_nop 0
	v_cndmask_b32_e32 v49, 0, v49, vcc
	v_cmp_ngt_f32_e32 vcc, 0xc2b17218, v45
	s_nop 1
	v_cndmask_b32_e32 v49, v192, v49, vcc
	v_mul_f32_e32 v52, 0xbfb8aa3b, v46
	v_fma_f32 v53, v46, s20, -v52
	v_rndne_f32_e32 v54, v52
	v_fmac_f32_e32 v53, 0xb2a5705f, v46
	v_sub_f32_e32 v52, v52, v54
	v_add_f32_e32 v52, v52, v53
	v_exp_f32_e32 v50, v52
	v_cvt_i32_f32_e32 v54, v54
	v_cmp_nlt_f32_e32 vcc, 0x42ce8ed0, v46
	v_ldexp_f32 v50, v50, v54
	s_nop 0
	v_cndmask_b32_e32 v50, 0, v50, vcc
	v_cmp_ngt_f32_e32 vcc, 0xc2b17218, v46
	s_nop 1
	v_cndmask_b32_e32 v50, v192, v50, vcc
	v_mul_f32_e32 v52, 0xbfb8aa3b, v47
	v_fma_f32 v53, v47, s20, -v52
	v_rndne_f32_e32 v54, v52
	v_fmac_f32_e32 v53, 0xb2a5705f, v47
	v_sub_f32_e32 v52, v52, v54
	v_add_f32_e32 v52, v52, v53
	v_exp_f32_e32 v51, v52
	v_cvt_i32_f32_e32 v54, v54
	v_cmp_nlt_f32_e32 vcc, 0x42ce8ed0, v47
	v_ldexp_f32 v51, v51, v54
	s_nop 0
	v_cndmask_b32_e32 v51, 0, v51, vcc
	v_cmp_ngt_f32_e32 vcc, 0xc2b17218, v47
	s_nop 1
	v_cndmask_b32_e32 v51, v192, v51, vcc
	v_pk_add_f32 v[48:49], v[48:49], 1.0 op_sel_hi:[1,0]
	v_pk_add_f32 v[50:51], v[50:51], 1.0 op_sel_hi:[1,0]
	v_div_scale_f32 v52, s[2:3], v48, v48, v44
	v_rcp_f32_e32 v53, v52
	s_nop 0
	v_fma_f32 v54, -v52, v53, 1.0
	v_fmac_f32_e32 v53, v54, v53
	v_div_scale_f32 v54, vcc, v44, v48, v44
	v_mul_f32_e32 v55, v54, v53
	v_fma_f32 v40, -v52, v55, v54
	v_fmac_f32_e32 v55, v40, v53
	v_fma_f32 v52, -v52, v55, v54
	v_div_fmas_f32 v52, v52, v53, v55
	v_div_fixup_f32 v40, v52, v48, v44
	v_div_scale_f32 v52, s[2:3], v49, v49, v45
	v_rcp_f32_e32 v53, v52
	s_nop 0
	v_fma_f32 v54, -v52, v53, 1.0
	v_fmac_f32_e32 v53, v54, v53
	v_div_scale_f32 v54, vcc, v45, v49, v45
	v_mul_f32_e32 v55, v54, v53
	v_fma_f32 v41, -v52, v55, v54
	v_fmac_f32_e32 v55, v41, v53
	v_fma_f32 v52, -v52, v55, v54
	v_div_fmas_f32 v52, v52, v53, v55
	v_div_fixup_f32 v41, v52, v49, v45
	v_div_scale_f32 v52, s[2:3], v50, v50, v46
	v_rcp_f32_e32 v53, v52
	s_nop 0
	v_fma_f32 v54, -v52, v53, 1.0
	v_fmac_f32_e32 v53, v54, v53
	v_div_scale_f32 v54, vcc, v46, v50, v46
	v_mul_f32_e32 v55, v54, v53
	v_fma_f32 v42, -v52, v55, v54
	v_fmac_f32_e32 v55, v42, v53
	v_fma_f32 v52, -v52, v55, v54
	v_div_fmas_f32 v52, v52, v53, v55
	v_div_fixup_f32 v42, v52, v50, v46
	v_div_scale_f32 v52, s[2:3], v51, v51, v47
	v_rcp_f32_e32 v53, v52
	s_nop 0
	v_fma_f32 v54, -v52, v53, 1.0
	v_fmac_f32_e32 v53, v54, v53
	v_div_scale_f32 v54, vcc, v47, v51, v47
	v_mul_f32_e32 v55, v54, v53
	v_fma_f32 v43, -v52, v55, v54
	v_fmac_f32_e32 v55, v43, v53
	v_fma_f32 v52, -v52, v55, v54
	v_div_fmas_f32 v52, v52, v53, v55
	v_div_fixup_f32 v43, v52, v51, v47
	v_fmamk_f32 v34, v34, 0x3b800000, v177
	v_mul_f32_e32 v35, 0x4b800000, v34
	v_cmp_gt_f32_e32 vcc, 0x800000, v34
	s_nop 1
	v_cndmask_b32_e32 v34, v34, v35, vcc
	v_rsq_f32_e32 v38, v34
	s_nop 0
	v_mul_f32_e32 v35, 0x45800000, v38
	v_cndmask_b32_e32 v38, v38, v35, vcc
	v_pk_mul_f32 v[32:33], v[32:33], v[38:39] op_sel_hi:[1,0]
	v_pk_mul_f32 v[36:37], v[36:37], v[38:39] op_sel_hi:[1,0]
	v_pk_mul_f32 v[32:33], v[0:1], v[32:33]
	v_pk_mul_f32 v[36:37], v[2:3], v[36:37]
	v_pk_mul_f32 v[32:33], v[40:41], v[32:33]
	v_pk_mul_f32 v[36:37], v[42:43], v[36:37]
	v_cvt_pk_bf16_f32 v56, v32, v33
	v_cvt_pk_bf16_f32 v57, v36, v37
	s_lshl_b32 s0, s21, 2
	s_lshl_b32 s1, s0, 20
	s_add_u32 s16, s14, s1
	s_addc_u32 s17, s15, 0
	global_store_dwordx2 v4, v[56:57], s[16:17]
	s_waitcnt vmcnt(13)
	v_lshlrev_b32_e32 v32, 16, v14
	v_and_b32_e32 v33, 0xffff0000, v14
	v_lshlrev_b32_e32 v34, 16, v16
	v_and_b32_e32 v35, 0xffff0000, v16
	v_lshlrev_b32_e32 v36, 16, v15
	v_and_b32_e32 v37, 0xffff0000, v15
	v_lshlrev_b32_e32 v38, 16, v17
	v_and_b32_e32 v39, 0xffff0000, v17
	v_pk_add_f32 v[32:33], v[32:33], v[34:35]
	v_pk_add_f32 v[36:37], v[36:37], v[38:39]
	v_lshlrev_b32_e32 v44, 16, v18
	v_and_b32_e32 v45, 0xffff0000, v18
	v_lshlrev_b32_e32 v46, 16, v19
	v_and_b32_e32 v47, 0xffff0000, v19
	s_lshl_b32 s0, s21, 2
	s_add_i32 s0, s0, 5
	s_min_u32 s0, s0, 23
	s_lshl_b32 s1, s0, 20
	s_add_u32 s16, s6, s1
	s_addc_u32 s17, s7, 0
	s_add_u32 s18, s8, s1
	s_addc_u32 s19, s9, 0
	s_mul_i32 s1, s0, 0x300000
	s_add_u32 s12, s10, s1
	s_addc_u32 s13, s11, 0
	global_load_dwordx2 v[14:15], v4, s[16:17] nt
	global_load_dwordx2 v[16:17], v4, s[18:19] nt
	global_load_dwordx2 v[18:19], v4, s[12:13] nt
	v_pk_mul_f32 v[34:35], v[32:33], v[32:33]
	v_pk_mul_f32 v[38:39], v[36:37], v[36:37]
	v_add_f32_e32 v34, v34, v35
	v_add_f32_e32 v34, v34, v38
	v_add_f32_e32 v34, v34, v39
	s_nop 1
	v_add_f32_dpp v34, v34, v34 row_ror:8 row_mask:0xf bank_mask:0xf
	s_nop 1
	v_add_f32_dpp v34, v34, v34 row_ror:4 row_mask:0xf bank_mask:0xf
	s_nop 1
	v_add_f32_dpp v34, v34, v34 row_ror:2 row_mask:0xf bank_mask:0xf
	s_nop 1
	v_add_f32_dpp v34, v34, v34 row_ror:1 row_mask:0xf bank_mask:0xf
	v_mov_b32_e32 v35, v34
	s_nop 1
	v_permlane16_swap_b32 v34, v35
	v_add_f32_e32 v34, v34, v35
	v_mov_b32_e32 v35, v34
	s_nop 1
	v_permlane32_swap_b32 v34, v35
	v_add_f32_e32 v34, v34, v35
	v_mul_f32_e32 v52, 0xbfb8aa3b, v44
	v_fma_f32 v53, v44, s20, -v52
	v_rndne_f32_e32 v54, v52
	v_fmac_f32_e32 v53, 0xb2a5705f, v44
	v_sub_f32_e32 v52, v52, v54
	v_add_f32_e32 v52, v52, v53
	v_exp_f32_e32 v48, v52
	v_cvt_i32_f32_e32 v54, v54
	v_cmp_nlt_f32_e32 vcc, 0x42ce8ed0, v44
	v_ldexp_f32 v48, v48, v54
	s_nop 0
	v_cndmask_b32_e32 v48, 0, v48, vcc
	v_cmp_ngt_f32_e32 vcc, 0xc2b17218, v44
	s_nop 1
	v_cndmask_b32_e32 v48, v192, v48, vcc
	v_mul_f32_e32 v52, 0xbfb8aa3b, v45
	v_fma_f32 v53, v45, s20, -v52
	v_rndne_f32_e32 v54, v52
	v_fmac_f32_e32 v53, 0xb2a5705f, v45
	v_sub_f32_e32 v52, v52, v54
	v_add_f32_e32 v52, v52, v53
	v_exp_f32_e32 v49, v52
	v_cvt_i32_f32_e32 v54, v54
	v_cmp_nlt_f32_e32 vcc, 0x42ce8ed0, v45
	v_ldexp_f32 v49, v49, v54
	s_nop 0
	v_cndmask_b32_e32 v49, 0, v49, vcc
	v_cmp_ngt_f32_e32 vcc, 0xc2b17218, v45
	s_nop 1
	v_cndmask_b32_e32 v49, v192, v49, vcc
	v_mul_f32_e32 v52, 0xbfb8aa3b, v46
	v_fma_f32 v53, v46, s20, -v52
	v_rndne_f32_e32 v54, v52
	v_fmac_f32_e32 v53, 0xb2a5705f, v46
	v_sub_f32_e32 v52, v52, v54
	v_add_f32_e32 v52, v52, v53
	v_exp_f32_e32 v50, v52
	v_cvt_i32_f32_e32 v54, v54
	v_cmp_nlt_f32_e32 vcc, 0x42ce8ed0, v46
	v_ldexp_f32 v50, v50, v54
	s_nop 0
	v_cndmask_b32_e32 v50, 0, v50, vcc
	v_cmp_ngt_f32_e32 vcc, 0xc2b17218, v46
	s_nop 1
	v_cndmask_b32_e32 v50, v192, v50, vcc
	v_mul_f32_e32 v52, 0xbfb8aa3b, v47
	v_fma_f32 v53, v47, s20, -v52
	v_rndne_f32_e32 v54, v52
	v_fmac_f32_e32 v53, 0xb2a5705f, v47
	v_sub_f32_e32 v52, v52, v54
	v_add_f32_e32 v52, v52, v53
	v_exp_f32_e32 v51, v52
	v_cvt_i32_f32_e32 v54, v54
	v_cmp_nlt_f32_e32 vcc, 0x42ce8ed0, v47
	v_ldexp_f32 v51, v51, v54
	s_nop 0
	v_cndmask_b32_e32 v51, 0, v51, vcc
	v_cmp_ngt_f32_e32 vcc, 0xc2b17218, v47
	s_nop 1
	v_cndmask_b32_e32 v51, v192, v51, vcc
	v_pk_add_f32 v[48:49], v[48:49], 1.0 op_sel_hi:[1,0]
	v_pk_add_f32 v[50:51], v[50:51], 1.0 op_sel_hi:[1,0]
	v_div_scale_f32 v52, s[2:3], v48, v48, v44
	v_rcp_f32_e32 v53, v52
	s_nop 0
	v_fma_f32 v54, -v52, v53, 1.0
	v_fmac_f32_e32 v53, v54, v53
	v_div_scale_f32 v54, vcc, v44, v48, v44
	v_mul_f32_e32 v55, v54, v53
	v_fma_f32 v40, -v52, v55, v54
	v_fmac_f32_e32 v55, v40, v53
	v_fma_f32 v52, -v52, v55, v54
	v_div_fmas_f32 v52, v52, v53, v55
	v_div_fixup_f32 v40, v52, v48, v44
	v_div_scale_f32 v52, s[2:3], v49, v49, v45
	v_rcp_f32_e32 v53, v52
	s_nop 0
	v_fma_f32 v54, -v52, v53, 1.0
	v_fmac_f32_e32 v53, v54, v53
	v_div_scale_f32 v54, vcc, v45, v49, v45
	v_mul_f32_e32 v55, v54, v53
	v_fma_f32 v41, -v52, v55, v54
	v_fmac_f32_e32 v55, v41, v53
	v_fma_f32 v52, -v52, v55, v54
	v_div_fmas_f32 v52, v52, v53, v55
	v_div_fixup_f32 v41, v52, v49, v45
	v_div_scale_f32 v52, s[2:3], v50, v50, v46
	v_rcp_f32_e32 v53, v52
	s_nop 0
	v_fma_f32 v54, -v52, v53, 1.0
	v_fmac_f32_e32 v53, v54, v53
	v_div_scale_f32 v54, vcc, v46, v50, v46
	v_mul_f32_e32 v55, v54, v53
	v_fma_f32 v42, -v52, v55, v54
	v_fmac_f32_e32 v55, v42, v53
	v_fma_f32 v52, -v52, v55, v54
	v_div_fmas_f32 v52, v52, v53, v55
	v_div_fixup_f32 v42, v52, v50, v46
	v_div_scale_f32 v52, s[2:3], v51, v51, v47
	v_rcp_f32_e32 v53, v52
	s_nop 0
	v_fma_f32 v54, -v52, v53, 1.0
	v_fmac_f32_e32 v53, v54, v53
	v_div_scale_f32 v54, vcc, v47, v51, v47
	v_mul_f32_e32 v55, v54, v53
	v_fma_f32 v43, -v52, v55, v54
	v_fmac_f32_e32 v55, v43, v53
	v_fma_f32 v52, -v52, v55, v54
	v_div_fmas_f32 v52, v52, v53, v55
	v_div_fixup_f32 v43, v52, v51, v47
	v_fmamk_f32 v34, v34, 0x3b800000, v177
	v_mul_f32_e32 v35, 0x4b800000, v34
	v_cmp_gt_f32_e32 vcc, 0x800000, v34
	s_nop 1
	v_cndmask_b32_e32 v34, v34, v35, vcc
	v_rsq_f32_e32 v38, v34
	s_nop 0
	v_mul_f32_e32 v35, 0x45800000, v38
	v_cndmask_b32_e32 v38, v38, v35, vcc
	v_pk_mul_f32 v[32:33], v[32:33], v[38:39] op_sel_hi:[1,0]
	v_pk_mul_f32 v[36:37], v[36:37], v[38:39] op_sel_hi:[1,0]
	v_pk_mul_f32 v[32:33], v[0:1], v[32:33]
	v_pk_mul_f32 v[36:37], v[2:3], v[36:37]
	v_pk_mul_f32 v[32:33], v[40:41], v[32:33]
	v_pk_mul_f32 v[36:37], v[42:43], v[36:37]
	v_cvt_pk_bf16_f32 v56, v32, v33
	v_cvt_pk_bf16_f32 v57, v36, v37
	s_lshl_b32 s0, s21, 2
	s_add_i32 s0, s0, 1
	s_lshl_b32 s1, s0, 20
	s_add_u32 s16, s14, s1
	s_addc_u32 s17, s15, 0
	global_store_dwordx2 v4, v[56:57], s[16:17]
	s_waitcnt vmcnt(13)
	v_lshlrev_b32_e32 v32, 16, v20
	v_and_b32_e32 v33, 0xffff0000, v20
	v_lshlrev_b32_e32 v34, 16, v22
	v_and_b32_e32 v35, 0xffff0000, v22
	v_lshlrev_b32_e32 v36, 16, v21
	v_and_b32_e32 v37, 0xffff0000, v21
	v_lshlrev_b32_e32 v38, 16, v23
	v_and_b32_e32 v39, 0xffff0000, v23
	v_pk_add_f32 v[32:33], v[32:33], v[34:35]
	v_pk_add_f32 v[36:37], v[36:37], v[38:39]
	v_lshlrev_b32_e32 v44, 16, v24
	v_and_b32_e32 v45, 0xffff0000, v24
	v_lshlrev_b32_e32 v46, 16, v25
	v_and_b32_e32 v47, 0xffff0000, v25
	s_lshl_b32 s0, s21, 2
	s_add_i32 s0, s0, 6
	s_min_u32 s0, s0, 23
	s_lshl_b32 s1, s0, 20
	s_add_u32 s16, s6, s1
	s_addc_u32 s17, s7, 0
	s_add_u32 s18, s8, s1
	s_addc_u32 s19, s9, 0
	s_mul_i32 s1, s0, 0x300000
	s_add_u32 s12, s10, s1
	s_addc_u32 s13, s11, 0
	global_load_dwordx2 v[20:21], v4, s[16:17] nt
	global_load_dwordx2 v[22:23], v4, s[18:19] nt
	global_load_dwordx2 v[24:25], v4, s[12:13] nt
	v_pk_mul_f32 v[34:35], v[32:33], v[32:33]
	v_pk_mul_f32 v[38:39], v[36:37], v[36:37]
	v_add_f32_e32 v34, v34, v35
	v_add_f32_e32 v34, v34, v38
	v_add_f32_e32 v34, v34, v39
	s_nop 1
	v_add_f32_dpp v34, v34, v34 row_ror:8 row_mask:0xf bank_mask:0xf
	s_nop 1
	v_add_f32_dpp v34, v34, v34 row_ror:4 row_mask:0xf bank_mask:0xf
	s_nop 1
	v_add_f32_dpp v34, v34, v34 row_ror:2 row_mask:0xf bank_mask:0xf
	s_nop 1
	v_add_f32_dpp v34, v34, v34 row_ror:1 row_mask:0xf bank_mask:0xf
	v_mov_b32_e32 v35, v34
	s_nop 1
	v_permlane16_swap_b32 v34, v35
	v_add_f32_e32 v34, v34, v35
	v_mov_b32_e32 v35, v34
	s_nop 1
	v_permlane32_swap_b32 v34, v35
	v_add_f32_e32 v34, v34, v35
	v_mul_f32_e32 v52, 0xbfb8aa3b, v44
	v_fma_f32 v53, v44, s20, -v52
	v_rndne_f32_e32 v54, v52
	v_fmac_f32_e32 v53, 0xb2a5705f, v44
	v_sub_f32_e32 v52, v52, v54
	v_add_f32_e32 v52, v52, v53
	v_exp_f32_e32 v48, v52
	v_cvt_i32_f32_e32 v54, v54
	v_cmp_nlt_f32_e32 vcc, 0x42ce8ed0, v44
	v_ldexp_f32 v48, v48, v54
	s_nop 0
	v_cndmask_b32_e32 v48, 0, v48, vcc
	v_cmp_ngt_f32_e32 vcc, 0xc2b17218, v44
	s_nop 1
	v_cndmask_b32_e32 v48, v192, v48, vcc
	v_mul_f32_e32 v52, 0xbfb8aa3b, v45
	v_fma_f32 v53, v45, s20, -v52
	v_rndne_f32_e32 v54, v52
	v_fmac_f32_e32 v53, 0xb2a5705f, v45
	v_sub_f32_e32 v52, v52, v54
	v_add_f32_e32 v52, v52, v53
	v_exp_f32_e32 v49, v52
	v_cvt_i32_f32_e32 v54, v54
	v_cmp_nlt_f32_e32 vcc, 0x42ce8ed0, v45
	v_ldexp_f32 v49, v49, v54
	s_nop 0
	v_cndmask_b32_e32 v49, 0, v49, vcc
	v_cmp_ngt_f32_e32 vcc, 0xc2b17218, v45
	s_nop 1
	v_cndmask_b32_e32 v49, v192, v49, vcc
	v_mul_f32_e32 v52, 0xbfb8aa3b, v46
	v_fma_f32 v53, v46, s20, -v52
	v_rndne_f32_e32 v54, v52
	v_fmac_f32_e32 v53, 0xb2a5705f, v46
	v_sub_f32_e32 v52, v52, v54
	v_add_f32_e32 v52, v52, v53
	v_exp_f32_e32 v50, v52
	v_cvt_i32_f32_e32 v54, v54
	v_cmp_nlt_f32_e32 vcc, 0x42ce8ed0, v46
	v_ldexp_f32 v50, v50, v54
	s_nop 0
	v_cndmask_b32_e32 v50, 0, v50, vcc
	v_cmp_ngt_f32_e32 vcc, 0xc2b17218, v46
	s_nop 1
	v_cndmask_b32_e32 v50, v192, v50, vcc
	v_mul_f32_e32 v52, 0xbfb8aa3b, v47
	v_fma_f32 v53, v47, s20, -v52
	v_rndne_f32_e32 v54, v52
	v_fmac_f32_e32 v53, 0xb2a5705f, v47
	v_sub_f32_e32 v52, v52, v54
	v_add_f32_e32 v52, v52, v53
	v_exp_f32_e32 v51, v52
	v_cvt_i32_f32_e32 v54, v54
	v_cmp_nlt_f32_e32 vcc, 0x42ce8ed0, v47
	v_ldexp_f32 v51, v51, v54
	s_nop 0
	v_cndmask_b32_e32 v51, 0, v51, vcc
	v_cmp_ngt_f32_e32 vcc, 0xc2b17218, v47
	s_nop 1
	v_cndmask_b32_e32 v51, v192, v51, vcc
	v_pk_add_f32 v[48:49], v[48:49], 1.0 op_sel_hi:[1,0]
	v_pk_add_f32 v[50:51], v[50:51], 1.0 op_sel_hi:[1,0]
	v_div_scale_f32 v52, s[2:3], v48, v48, v44
	v_rcp_f32_e32 v53, v52
	s_nop 0
	v_fma_f32 v54, -v52, v53, 1.0
	v_fmac_f32_e32 v53, v54, v53
	v_div_scale_f32 v54, vcc, v44, v48, v44
	v_mul_f32_e32 v55, v54, v53
	v_fma_f32 v40, -v52, v55, v54
	v_fmac_f32_e32 v55, v40, v53
	v_fma_f32 v52, -v52, v55, v54
	v_div_fmas_f32 v52, v52, v53, v55
	v_div_fixup_f32 v40, v52, v48, v44
	v_div_scale_f32 v52, s[2:3], v49, v49, v45
	v_rcp_f32_e32 v53, v52
	s_nop 0
	v_fma_f32 v54, -v52, v53, 1.0
	v_fmac_f32_e32 v53, v54, v53
	v_div_scale_f32 v54, vcc, v45, v49, v45
	v_mul_f32_e32 v55, v54, v53
	v_fma_f32 v41, -v52, v55, v54
	v_fmac_f32_e32 v55, v41, v53
	v_fma_f32 v52, -v52, v55, v54
	v_div_fmas_f32 v52, v52, v53, v55
	v_div_fixup_f32 v41, v52, v49, v45
	v_div_scale_f32 v52, s[2:3], v50, v50, v46
	v_rcp_f32_e32 v53, v52
	s_nop 0
	v_fma_f32 v54, -v52, v53, 1.0
	v_fmac_f32_e32 v53, v54, v53
	v_div_scale_f32 v54, vcc, v46, v50, v46
	v_mul_f32_e32 v55, v54, v53
	v_fma_f32 v42, -v52, v55, v54
	v_fmac_f32_e32 v55, v42, v53
	v_fma_f32 v52, -v52, v55, v54
	v_div_fmas_f32 v52, v52, v53, v55
	v_div_fixup_f32 v42, v52, v50, v46
	v_div_scale_f32 v52, s[2:3], v51, v51, v47
	v_rcp_f32_e32 v53, v52
	s_nop 0
	v_fma_f32 v54, -v52, v53, 1.0
	v_fmac_f32_e32 v53, v54, v53
	v_div_scale_f32 v54, vcc, v47, v51, v47
	v_mul_f32_e32 v55, v54, v53
	v_fma_f32 v43, -v52, v55, v54
	v_fmac_f32_e32 v55, v43, v53
	v_fma_f32 v52, -v52, v55, v54
	v_div_fmas_f32 v52, v52, v53, v55
	v_div_fixup_f32 v43, v52, v51, v47
	v_fmamk_f32 v34, v34, 0x3b800000, v177
	v_mul_f32_e32 v35, 0x4b800000, v34
	v_cmp_gt_f32_e32 vcc, 0x800000, v34
	s_nop 1
	v_cndmask_b32_e32 v34, v34, v35, vcc
	v_rsq_f32_e32 v38, v34
	s_nop 0
	v_mul_f32_e32 v35, 0x45800000, v38
	v_cndmask_b32_e32 v38, v38, v35, vcc
	v_pk_mul_f32 v[32:33], v[32:33], v[38:39] op_sel_hi:[1,0]
	v_pk_mul_f32 v[36:37], v[36:37], v[38:39] op_sel_hi:[1,0]
	v_pk_mul_f32 v[32:33], v[0:1], v[32:33]
	v_pk_mul_f32 v[36:37], v[2:3], v[36:37]
	v_pk_mul_f32 v[32:33], v[40:41], v[32:33]
	v_pk_mul_f32 v[36:37], v[42:43], v[36:37]
	v_cvt_pk_bf16_f32 v56, v32, v33
	v_cvt_pk_bf16_f32 v57, v36, v37
	s_lshl_b32 s0, s21, 2
	s_add_i32 s0, s0, 2
	s_lshl_b32 s1, s0, 20
	s_add_u32 s16, s14, s1
	s_addc_u32 s17, s15, 0
	global_store_dwordx2 v4, v[56:57], s[16:17]
	s_waitcnt vmcnt(13)
	v_lshlrev_b32_e32 v32, 16, v26
	v_and_b32_e32 v33, 0xffff0000, v26
	v_lshlrev_b32_e32 v34, 16, v28
	v_and_b32_e32 v35, 0xffff0000, v28
	v_lshlrev_b32_e32 v36, 16, v27
	v_and_b32_e32 v37, 0xffff0000, v27
	v_lshlrev_b32_e32 v38, 16, v29
	v_and_b32_e32 v39, 0xffff0000, v29
	v_pk_add_f32 v[32:33], v[32:33], v[34:35]
	v_pk_add_f32 v[36:37], v[36:37], v[38:39]
	v_lshlrev_b32_e32 v44, 16, v30
	v_and_b32_e32 v45, 0xffff0000, v30
	v_lshlrev_b32_e32 v46, 16, v31
	v_and_b32_e32 v47, 0xffff0000, v31
	s_lshl_b32 s0, s21, 2
	s_add_i32 s0, s0, 7
	s_min_u32 s0, s0, 23
	s_lshl_b32 s1, s0, 20
	s_add_u32 s16, s6, s1
	s_addc_u32 s17, s7, 0
	s_add_u32 s18, s8, s1
	s_addc_u32 s19, s9, 0
	s_mul_i32 s1, s0, 0x300000
	s_add_u32 s12, s10, s1
	s_addc_u32 s13, s11, 0
	global_load_dwordx2 v[26:27], v4, s[16:17] nt
	global_load_dwordx2 v[28:29], v4, s[18:19] nt
	global_load_dwordx2 v[30:31], v4, s[12:13] nt
	v_pk_mul_f32 v[34:35], v[32:33], v[32:33]
	v_pk_mul_f32 v[38:39], v[36:37], v[36:37]
	v_add_f32_e32 v34, v34, v35
	v_add_f32_e32 v34, v34, v38
	v_add_f32_e32 v34, v34, v39
	s_nop 1
	v_add_f32_dpp v34, v34, v34 row_ror:8 row_mask:0xf bank_mask:0xf
	s_nop 1
	v_add_f32_dpp v34, v34, v34 row_ror:4 row_mask:0xf bank_mask:0xf
	s_nop 1
	v_add_f32_dpp v34, v34, v34 row_ror:2 row_mask:0xf bank_mask:0xf
	s_nop 1
	v_add_f32_dpp v34, v34, v34 row_ror:1 row_mask:0xf bank_mask:0xf
	v_mov_b32_e32 v35, v34
	s_nop 1
	v_permlane16_swap_b32 v34, v35
	v_add_f32_e32 v34, v34, v35
	v_mov_b32_e32 v35, v34
	s_nop 1
	v_permlane32_swap_b32 v34, v35
	v_add_f32_e32 v34, v34, v35
	v_mul_f32_e32 v52, 0xbfb8aa3b, v44
	v_fma_f32 v53, v44, s20, -v52
	v_rndne_f32_e32 v54, v52
	v_fmac_f32_e32 v53, 0xb2a5705f, v44
	v_sub_f32_e32 v52, v52, v54
	v_add_f32_e32 v52, v52, v53
	v_exp_f32_e32 v48, v52
	v_cvt_i32_f32_e32 v54, v54
	v_cmp_nlt_f32_e32 vcc, 0x42ce8ed0, v44
	v_ldexp_f32 v48, v48, v54
	s_nop 0
	v_cndmask_b32_e32 v48, 0, v48, vcc
	v_cmp_ngt_f32_e32 vcc, 0xc2b17218, v44
	s_nop 1
	v_cndmask_b32_e32 v48, v192, v48, vcc
	v_mul_f32_e32 v52, 0xbfb8aa3b, v45
	v_fma_f32 v53, v45, s20, -v52
	v_rndne_f32_e32 v54, v52
	v_fmac_f32_e32 v53, 0xb2a5705f, v45
	v_sub_f32_e32 v52, v52, v54
	v_add_f32_e32 v52, v52, v53
	v_exp_f32_e32 v49, v52
	v_cvt_i32_f32_e32 v54, v54
	v_cmp_nlt_f32_e32 vcc, 0x42ce8ed0, v45
	v_ldexp_f32 v49, v49, v54
	s_nop 0
	v_cndmask_b32_e32 v49, 0, v49, vcc
	v_cmp_ngt_f32_e32 vcc, 0xc2b17218, v45
	s_nop 1
	v_cndmask_b32_e32 v49, v192, v49, vcc
	v_mul_f32_e32 v52, 0xbfb8aa3b, v46
	v_fma_f32 v53, v46, s20, -v52
	v_rndne_f32_e32 v54, v52
	v_fmac_f32_e32 v53, 0xb2a5705f, v46
	v_sub_f32_e32 v52, v52, v54
	v_add_f32_e32 v52, v52, v53
	v_exp_f32_e32 v50, v52
	v_cvt_i32_f32_e32 v54, v54
	v_cmp_nlt_f32_e32 vcc, 0x42ce8ed0, v46
	v_ldexp_f32 v50, v50, v54
	s_nop 0
	v_cndmask_b32_e32 v50, 0, v50, vcc
	v_cmp_ngt_f32_e32 vcc, 0xc2b17218, v46
	s_nop 1
	v_cndmask_b32_e32 v50, v192, v50, vcc
	v_mul_f32_e32 v52, 0xbfb8aa3b, v47
	v_fma_f32 v53, v47, s20, -v52
	v_rndne_f32_e32 v54, v52
	v_fmac_f32_e32 v53, 0xb2a5705f, v47
	v_sub_f32_e32 v52, v52, v54
	v_add_f32_e32 v52, v52, v53
	v_exp_f32_e32 v51, v52
	v_cvt_i32_f32_e32 v54, v54
	v_cmp_nlt_f32_e32 vcc, 0x42ce8ed0, v47
	v_ldexp_f32 v51, v51, v54
	s_nop 0
	v_cndmask_b32_e32 v51, 0, v51, vcc
	v_cmp_ngt_f32_e32 vcc, 0xc2b17218, v47
	s_nop 1
	v_cndmask_b32_e32 v51, v192, v51, vcc
	v_pk_add_f32 v[48:49], v[48:49], 1.0 op_sel_hi:[1,0]
	v_pk_add_f32 v[50:51], v[50:51], 1.0 op_sel_hi:[1,0]
	v_div_scale_f32 v52, s[2:3], v48, v48, v44
	v_rcp_f32_e32 v53, v52
	s_nop 0
	v_fma_f32 v54, -v52, v53, 1.0
	v_fmac_f32_e32 v53, v54, v53
	v_div_scale_f32 v54, vcc, v44, v48, v44
	v_mul_f32_e32 v55, v54, v53
	v_fma_f32 v40, -v52, v55, v54
	v_fmac_f32_e32 v55, v40, v53
	v_fma_f32 v52, -v52, v55, v54
	v_div_fmas_f32 v52, v52, v53, v55
	v_div_fixup_f32 v40, v52, v48, v44
	v_div_scale_f32 v52, s[2:3], v49, v49, v45
	v_rcp_f32_e32 v53, v52
	s_nop 0
	v_fma_f32 v54, -v52, v53, 1.0
	v_fmac_f32_e32 v53, v54, v53
	v_div_scale_f32 v54, vcc, v45, v49, v45
	v_mul_f32_e32 v55, v54, v53
	v_fma_f32 v41, -v52, v55, v54
	v_fmac_f32_e32 v55, v41, v53
	v_fma_f32 v52, -v52, v55, v54
	v_div_fmas_f32 v52, v52, v53, v55
	v_div_fixup_f32 v41, v52, v49, v45
	v_div_scale_f32 v52, s[2:3], v50, v50, v46
	v_rcp_f32_e32 v53, v52
	s_nop 0
	v_fma_f32 v54, -v52, v53, 1.0
	v_fmac_f32_e32 v53, v54, v53
	v_div_scale_f32 v54, vcc, v46, v50, v46
	v_mul_f32_e32 v55, v54, v53
	v_fma_f32 v42, -v52, v55, v54
	v_fmac_f32_e32 v55, v42, v53
	v_fma_f32 v52, -v52, v55, v54
	v_div_fmas_f32 v52, v52, v53, v55
	v_div_fixup_f32 v42, v52, v50, v46
	v_div_scale_f32 v52, s[2:3], v51, v51, v47
	v_rcp_f32_e32 v53, v52
	s_nop 0
	v_fma_f32 v54, -v52, v53, 1.0
	v_fmac_f32_e32 v53, v54, v53
	v_div_scale_f32 v54, vcc, v47, v51, v47
	v_mul_f32_e32 v55, v54, v53
	v_fma_f32 v43, -v52, v55, v54
	v_fmac_f32_e32 v55, v43, v53
	v_fma_f32 v52, -v52, v55, v54
	v_div_fmas_f32 v52, v52, v53, v55
	v_div_fixup_f32 v43, v52, v51, v47
	v_fmamk_f32 v34, v34, 0x3b800000, v177
	v_mul_f32_e32 v35, 0x4b800000, v34
	v_cmp_gt_f32_e32 vcc, 0x800000, v34
	s_nop 1
	v_cndmask_b32_e32 v34, v34, v35, vcc
	v_rsq_f32_e32 v38, v34
	s_nop 0
	v_mul_f32_e32 v35, 0x45800000, v38
	v_cndmask_b32_e32 v38, v38, v35, vcc
	v_pk_mul_f32 v[32:33], v[32:33], v[38:39] op_sel_hi:[1,0]
	v_pk_mul_f32 v[36:37], v[36:37], v[38:39] op_sel_hi:[1,0]
	v_pk_mul_f32 v[32:33], v[0:1], v[32:33]
	v_pk_mul_f32 v[36:37], v[2:3], v[36:37]
	v_pk_mul_f32 v[32:33], v[40:41], v[32:33]
	v_pk_mul_f32 v[36:37], v[42:43], v[36:37]
	v_cvt_pk_bf16_f32 v56, v32, v33
	v_cvt_pk_bf16_f32 v57, v36, v37
	s_lshl_b32 s0, s21, 2
	s_add_i32 s0, s0, 3
	s_lshl_b32 s1, s0, 20
	s_add_u32 s16, s14, s1
	s_addc_u32 s17, s15, 0
	global_store_dwordx2 v4, v[56:57], s[16:17]
	s_add_i32 s21, s21, 1
	s_cmp_lt_u32 s21, 6
	s_cbranch_scc1 .Lcomb_loop
	s_mov_b64 s[2:3], exec
	s_branch .LBB0_1242
